# P9 sample-row combine folded into the end of P8 (counter-signalled), final grid barrier and P9 phase removed
# baseline (speedup 1.0000x reference)
;     __device__ __forceinline__ void epi(Acc& acc, const Unit& u, int wr, int wc, int fr, int fq) const {
;     ...
;             float* pb = part + (size_t)(u.kind - 1) * 512 * DM;
; #pragma unroll
;             for (int ai = 0; ai < 2; ++ai)
; #pragma unroll
;                 for (int m = 0; m < 4; ++m) { const int srow = (u.pm - 128) * 256 + ai * 128 + rl0 + m * 16;
; #pragma unroll
;                     for (int bj = 0; bj < 2; ++bj) { const int col = u.pn * 256 + bj * 128 + wc * 32 + fq * 8;
;                         *(f32x4*)(pb + (size_t)srow * DM + col) = acc[ai][bj][m][0];
;                         *(f32x4*)(pb + (size_t)srow * DM + col + 4) = acc[ai][bj][m][1]; } }
.LBB0_1262:
	global_store_dwordx4 v[128:129], v[0:3], off offset:16
	s_waitcnt vmcnt(0)
	s_mov_b64 s[98:99], exec
	s_mov_b64 exec, 1
	v_mov_b32_e32 v222, 1
	v_mov_b32_e32 v223, 0
	s_add_u32 s100, s30, 0x2ff800
	s_addc_u32 s101, s31, 0
	global_atomic_add v223, v222, s[100:101] sc1
	s_mov_b64 exec, s[98:99]
	s_and_b64 vcc, exec, s[0:1]
	s_mov_b64 s[0:1], -1
	s_cbranch_vccnz .LBB0_1245
	s_branch .LBB0_1265

; __device__ __forceinline__ void sample_combine(const float* gate, const float* part, int nsk, int srow, f32x4 (&v)[4], int lane) {
; #pragma unroll
;     for (int j = 0; j < 4; ++j) { const int c4 = lane + 64 * j; f32x4 a = (f32x4){0.f, 0.f, 0.f, 0.f};
;         for (int k = 0; k < nsk; ++k) a += *((const f32x4*)(part + ((size_t)k * 512 + srow) * DM) + c4);
;         v[j] = v[j] + *((const f32x4*)gate + c4) * a; }
; }
; __global__ void __launch_bounds__(512, 2) mega_fwd(Args a) {
;     ...
;         for (int sr = bx * 8 + wid; sr < MS; sr += G * 8) { const int b16 = 8 + (sr >> 6); f32x4 v[4];
;             row_load_bf16(X1B + (size_t)(MP + sr) * DM, v, lane);
;             sample_combine(MOD + (size_t)b16 * 6144 + 5120, PART, 11, sr, v, lane);
; #pragma unroll
;             for (int j = 0; j < 4; ++j) *((f32x4*)(out + (size_t)(MP + sr) * DM) + lane + 64 * j) = v[j]; } }
.LBB0_1268:
	s_waitcnt vmcnt(0)
	s_cmpk_lt_i32 s2, 0x58
	s_cbranch_scc1 .Lp9f_end
	v_readfirstlane_b32 s0, v211
	s_ashr_i32 s0, s0, 6
	s_cmp_lg_u32 s0, 0
	s_cbranch_scc1 .Lp9f_go
	s_add_u32 s100, s30, 0x2ff800
	s_addc_u32 s101, s31, 0
	v_mov_b32_e32 v223, 0
	s_mov_b32 s98, 0
.Lp9f_poll:
	global_load_dword v222, v223, s[100:101] sc1
	s_waitcnt vmcnt(0)
	v_readfirstlane_b32 s99, v222
	s_cmpk_ge_u32 s99, 0x2c0
	s_cbranch_scc1 .Lp9f_inv
	s_add_i32 s98, s98, 1
	s_cmpk_gt_u32 s98, 0x12c
	s_cbranch_scc1 .Lp9f_inv
	s_sleep 8
	s_branch .Lp9f_poll
.Lp9f_inv:
	buffer_inv sc1
	s_waitcnt vmcnt(0)
.Lp9f_go:
	s_barrier
	v_readfirstlane_b32 s0, v211
	s_ashr_i32 s0, s0, 6
	s_sub_i32 s20, s2, 0x58
	s_lshl_b32 s20, s20, 3
	s_add_i32 s20, s20, s0
	v_and_b32_e32 v0, 63, v211
	v_lshlrev_b32_e32 v1, 4, v0
	v_lshlrev_b32_e32 v2, 3, v0
.Lp9f_loop:
	s_lshr_b32 s6, s20, 2
	s_and_b32 s7, s20, 3
	s_lshl_b32 s8, s6, 12
	s_lshl_b32 s9, s7, 10
	s_add_i32 s8, s8, s9
	s_add_u32 s10, s30, 0x1aa00000
	s_addc_u32 s11, s31, 0
	s_add_u32 s10, s10, s8
	s_addc_u32 s11, s11, 0
	global_load_dwordx4 v[8:11], v1, s[10:11]
	s_add_u32 s10, s10, 0x200000
	s_addc_u32 s11, s11, 0
	global_load_dwordx4 v[12:15], v1, s[10:11]
	s_add_u32 s10, s10, 0x200000
	s_addc_u32 s11, s11, 0
	global_load_dwordx4 v[16:19], v1, s[10:11]
	s_add_u32 s10, s10, 0x200000
	s_addc_u32 s11, s11, 0
	global_load_dwordx4 v[20:23], v1, s[10:11]
	s_add_u32 s10, s10, 0x200000
	s_addc_u32 s11, s11, 0
	global_load_dwordx4 v[24:27], v1, s[10:11]
	s_add_u32 s10, s10, 0x200000
	s_addc_u32 s11, s11, 0
	global_load_dwordx4 v[28:31], v1, s[10:11]
	s_add_u32 s10, s10, 0x200000
	s_addc_u32 s11, s11, 0
	global_load_dwordx4 v[32:35], v1, s[10:11]
	s_add_u32 s10, s10, 0x200000
	s_addc_u32 s11, s11, 0
	global_load_dwordx4 v[36:39], v1, s[10:11]
	s_add_u32 s10, s10, 0x200000
	s_addc_u32 s11, s11, 0
	global_load_dwordx4 v[40:43], v1, s[10:11]
	s_add_u32 s10, s10, 0x200000
	s_addc_u32 s11, s11, 0
	global_load_dwordx4 v[44:47], v1, s[10:11]
	s_add_u32 s10, s10, 0x200000
	s_addc_u32 s11, s11, 0
	global_load_dwordx4 v[48:51], v1, s[10:11]
	s_add_i32 s12, s6, 0x8000
	s_lshl_b32 s13, s12, 11
	s_lshl_b32 s14, s7, 9
	s_add_i32 s13, s13, s14
	s_add_u32 s14, s30, 0x15900000
	s_addc_u32 s15, s31, 0
	s_add_u32 s14, s14, s13
	s_addc_u32 s15, s15, 0
	global_load_dwordx2 v[52:53], v2, s[14:15]
	s_lshr_b32 s16, s6, 6
	s_add_i32 s16, s16, 8
	s_mul_i32 s16, s16, 0x6000
	s_add_i32 s16, s16, 0x5000
	s_add_i32 s16, s16, s9
	s_add_u32 s18, s30, s16
	s_addc_u32 s19, s31, 0
	global_load_dwordx4 v[56:59], v1, s[18:19]
	s_lshl_b32 s13, s12, 12
	s_lshr_b32 s14, s12, 20
	s_add_i32 s13, s13, s9
	s_add_u32 s16, s28, s13
	s_addc_u32 s17, s29, s14
	s_waitcnt vmcnt(11)
	v_pk_add_f32 v[8:9], v[8:9], v[12:13]
	v_pk_add_f32 v[10:11], v[10:11], v[14:15]
	s_waitcnt vmcnt(10)
	v_pk_add_f32 v[8:9], v[8:9], v[16:17]
	v_pk_add_f32 v[10:11], v[10:11], v[18:19]
	s_waitcnt vmcnt(9)
	v_pk_add_f32 v[8:9], v[8:9], v[20:21]
	v_pk_add_f32 v[10:11], v[10:11], v[22:23]
	s_waitcnt vmcnt(8)
	v_pk_add_f32 v[8:9], v[8:9], v[24:25]
	v_pk_add_f32 v[10:11], v[10:11], v[26:27]
	s_waitcnt vmcnt(7)
	v_pk_add_f32 v[8:9], v[8:9], v[28:29]
	v_pk_add_f32 v[10:11], v[10:11], v[30:31]
	s_waitcnt vmcnt(6)
	v_pk_add_f32 v[8:9], v[8:9], v[32:33]
	v_pk_add_f32 v[10:11], v[10:11], v[34:35]
	s_waitcnt vmcnt(5)
	v_pk_add_f32 v[8:9], v[8:9], v[36:37]
	v_pk_add_f32 v[10:11], v[10:11], v[38:39]
	s_waitcnt vmcnt(4)
	v_pk_add_f32 v[8:9], v[8:9], v[40:41]
	v_pk_add_f32 v[10:11], v[10:11], v[42:43]
	s_waitcnt vmcnt(3)
	v_pk_add_f32 v[8:9], v[8:9], v[44:45]
	v_pk_add_f32 v[10:11], v[10:11], v[46:47]
	s_waitcnt vmcnt(2)
	v_pk_add_f32 v[8:9], v[8:9], v[48:49]
	v_pk_add_f32 v[10:11], v[10:11], v[50:51]
	s_waitcnt vmcnt(1)
	v_lshlrev_b32_e32 v60, 16, v52
	v_and_b32_e32 v61, 0xffff0000, v52
	v_lshlrev_b32_e32 v62, 16, v53
	v_and_b32_e32 v63, 0xffff0000, v53
	s_waitcnt vmcnt(0)
	v_pk_fma_f32 v[8:9], v[8:9], v[56:57], v[60:61]
	v_pk_fma_f32 v[10:11], v[10:11], v[58:59], v[62:63]
	global_store_dwordx4 v1, v[8:11], s[16:17]
	s_addk_i32 s20, 0x540
	s_cmpk_lt_u32 s20, 0x800
	s_cbranch_scc1 .Lp9f_loop
	s_waitcnt vmcnt(0)
.Lp9f_end:
.LBB0_1323:
	s_endpgm
